# W2 conversion by workgroups 128-255 moved from the end of the SwiGLU GEMM phase to its start (desynchronises the two groups' epilogues)
# baseline (speedup 1.0000x reference)
.LBB0_1311:
	s_cmp_lt_i32 s86, 11
	s_cselect_b64 s[2:3], -1, 0
	s_and_b64 s[4:5], s[2:3], s[0:1]
	s_andn2_b64 vcc, exec, s[4:5]
	s_cbranch_vccnz .LBB0_1344
	s_cmp_lg_u32 s88, 0x100
	s_cbranch_scc1 .Ltail_skip
	s_cmp_lt_u32 s94, 0x80
	s_cbranch_scc1 .Ltail_skip
	v_writelane_b32 v228, s4, 18
	v_writelane_b32 v228, s5, 19
	v_readlane_b32 s0, v228, 12
	v_readlane_b32 s1, v228, 13
	s_sub_u32 s0, s0, 0xb0
	s_subb_u32 s1, s1, 0
	s_load_dwordx16 s[60:75], s[0:1], 0x0
	s_load_dwordx4 s[76:79], s[0:1], 0x80
	s_mov_b32 s101, 1
	s_movk_i32 s99, 0x44ff
	s_movk_i32 s100, 0x3a00
	s_waitcnt lgkmcnt(0)
	s_branch .Ltramp_fwd
.Ltail_return:
	v_readlane_b32 s4, v228, 18
	v_readlane_b32 s5, v228, 19
	s_add_u32 s62, s84, 0xb000000
	s_addc_u32 s63, s85, 0
	s_add_u32 s64, s84, 0xf800000
	s_addc_u32 s65, s85, 0
	s_add_u32 s70, s84, 0x13800000
	s_addc_u32 s71, s85, 0
	s_mov_b32 s101, 0
	s_waitcnt vmcnt(0) lgkmcnt(0)
	s_barrier
.Ltail_skip:
	s_abs_i32 s0, s88
	v_cvt_f32_u32_e32 v1, s0
	s_sub_i32 s2, 0, s0
	s_ashr_i32 s1, s88, 31
	v_readfirstlane_b32 s14, v165
	v_rcp_iflag_f32_e32 v1, v1
	s_nop 0
	v_mul_f32_e32 v1, 0x4f7ffffe, v1
	v_cvt_u32_f32_e32 v1, v1
	s_nop 0
	v_readfirstlane_b32 s3, v1
	s_mul_i32 s2, s2, s3
	s_mul_hi_u32 s2, s3, s2
	s_add_i32 s3, s3, s2
	s_mul_hi_u32 s2, s3, 0x580
	s_mul_i32 s3, s2, s0
	s_sub_i32 s3, 0x580, s3
	s_add_i32 s6, s2, 1
	s_sub_i32 s7, s3, s0
	s_cmp_ge_u32 s3, s0
	s_cselect_b32 s2, s6, s2
	s_cselect_b32 s3, s7, s3
	s_add_i32 s6, s2, 1
	s_cmp_ge_u32 s3, s0
	s_cselect_b32 s0, s6, s2
	s_xor_b32 s0, s0, s1
	s_sub_i32 s2, s0, s1
	s_mul_i32 s16, s2, s88
	s_sub_i32 s17, 0x580, s16
	s_cmp_lt_i32 s94, s17
	s_cselect_b64 s[6:7], -1, 0
	s_cmp_gt_i32 s2, 0
	s_mov_b64 s[0:1], -1
	s_mov_b32 s3, s94
	s_cbranch_scc1 .LBB0_1315
	s_cmp_eq_u32 s2, 0
	s_cselect_b64 s[0:1], -1, 0
	s_and_b64 s[0:1], s[0:1], s[6:7]
	s_and_b64 vcc, exec, s[0:1]
	s_cbranch_vccz .LBB0_1318
	s_abs_i32 s0, s17
	v_cvt_f32_u32_e32 v1, s0
	s_sub_i32 s8, 0, s0
	s_abs_i32 s3, s94
	s_ashr_i32 s1, s94, 31
	v_rcp_iflag_f32_e32 v1, v1
	s_nop 0
	v_mul_f32_e32 v1, 0x4f7ffffe, v1
	v_cvt_u32_f32_e32 v1, v1
	s_nop 0
	v_readfirstlane_b32 s9, v1
	s_mul_i32 s8, s8, s9
	s_mul_hi_u32 s8, s9, s8
	s_add_i32 s9, s9, s8
	s_mul_hi_u32 s8, s3, s9
	s_mul_i32 s8, s8, s0
	s_sub_i32 s3, s3, s8
	s_sub_i32 s8, s3, s0
	s_cmp_ge_u32 s3, s0
	s_cselect_b32 s3, s8, s3
	s_sub_i32 s8, s3, s0
	s_cmp_ge_u32 s3, s0
	s_cselect_b32 s0, s8, s3
	s_xor_b32 s0, s0, s1
	s_sub_i32 s3, s0, s1
	s_mov_b64 s[0:1], -1
